# plus: in-proj GEMM epilogue with hoisted row-scale/bias loads
# baseline (speedup 1.0000x reference)
; __device__ __forceinline__ unsigned pk2(float lo, float hi) { unsigned r; asm("v_cvt_pk_bf16_f32 %0, %1, %2" : "=v"(r) : "v"(lo), "v"(hi)); return r; }
;     __device__ __forceinline__ void operator()(const f32x4 (&acc)[2][2][4][2], const pg8::Unit& u, int wr, int wc, int fr, int fq) const {
;     ...
;         const int row0 = u.pm * 256 + wr * 64 + fr, col0 = u.pn * 256 + wc * 32 + 8 * fq;
;         const float* bp = bias + (size_t)((u.pm * 256) >> 14) * 5632 + col0;
;         f32x4 cb[2][2];
; #pragma unroll
;         for (int bj = 0; bj < 2; ++bj) { cb[bj][0] = *(const f32x4*)(bp + bj * 128); cb[bj][1] = *(const f32x4*)(bp + bj * 128 + 4); }
; #pragma unroll
;         for (int ai = 0; ai < 2; ++ai)
; #pragma unroll
;             for (int m = 0; m < 4; ++m) {
;                 const int row = row0 + ai * 128 + m * 16; const float rs = row_rs(ss, row);
; #pragma unroll
;                 for (int bj = 0; bj < 2; ++bj) {
;                     if (u.pn * 256 + bj * 128 + wc * 32 >= 2592) continue;
;                     const f32x4 v0 = acc[ai][bj][m][0] * rs + cb[bj][0], v1 = acc[ai][bj][m][1] * rs + cb[bj][1];
;                     u32x4 w; w.x = pk2(v0[0], v0[1]); w.y = pk2(v0[2], v0[3]); w.z = pk2(v1[0], v1[1]); w.w = pk2(v1[2], v1[3]);
;                     *(u32x4*)(O + (size_t)row * ldc + col0 + bj * 128) = w;
;                 }
.LBB0_222:
	s_lshl_b32 s0, s8, 8
	s_add_i32 s1, s0, s48
	s_lshl_b32 s0, s6, 8
	s_ashr_i32 s2, s8, 6
	s_or_b32 s0, s0, s49
	s_mul_hi_i32 s3, s2, 0x5800
	s_mulk_i32 s2, 0x5800
	s_add_u32 s2, s45, s2
	s_addc_u32 s3, s47, s3
	v_lshl_add_u32 v158, v167, 3, s0
	v_add_u32_e32 v162, s1, v166
	v_lshlrev_b32_e32 v159, 2, v158
	v_lshlrev_b32_e32 v163, 2, v162
	global_load_dwordx4 v[128:131], v159, s[2:3]
	global_load_dwordx4 v[132:135], v159, s[2:3] offset:16
	global_load_dwordx4 v[136:139], v159, s[2:3] offset:512
	global_load_dwordx4 v[140:143], v159, s[2:3] offset:528
	global_load_dword v170, v163, s[12:13]
	global_load_dword v172, v163, s[12:13] offset:64
	global_load_dword v174, v163, s[12:13] offset:128
	global_load_dword v176, v163, s[12:13] offset:192
	global_load_dword v178, v163, s[12:13] offset:512
	global_load_dword v180, v163, s[12:13] offset:576
	global_load_dword v182, v163, s[12:13] offset:640
	global_load_dword v184, v163, s[12:13] offset:704
	s_movk_i32 s1, 0x1600
	v_mul_lo_u32 v186, v162, s1
	v_lshl_add_u32 v186, v158, 1, v186
	v_add_u32_e32 v187, 0x16000, v186
	v_add_u32_e32 v188, 0x2c000, v186
	v_add_u32_e32 v189, 0x42000, v186
	v_add_u32_e32 v190, 0xb0000, v186
	v_add_u32_e32 v191, 0xc6000, v186
	v_add_u32_e32 v192, 0xdc000, v186
	v_add_u32_e32 v193, 0xf2000, v186
	s_waitcnt vmcnt(0)
	s_cmpk_gt_i32 s0, 0xa1f
	s_cbranch_scc1 .Lepst_bj1
	v_pk_fma_f32 v[124:125], v[124:125], v[170:171], v[128:129] op_sel_hi:[1,0,1]
	v_pk_fma_f32 v[126:127], v[126:127], v[170:171], v[130:131] op_sel_hi:[1,0,1]
	v_pk_fma_f32 v[120:121], v[120:121], v[170:171], v[132:133] op_sel_hi:[1,0,1]
	v_pk_fma_f32 v[122:123], v[122:123], v[170:171], v[134:135] op_sel_hi:[1,0,1]
	v_pk_fma_f32 v[108:109], v[108:109], v[172:173], v[128:129] op_sel_hi:[1,0,1]
	v_pk_fma_f32 v[110:111], v[110:111], v[172:173], v[130:131] op_sel_hi:[1,0,1]
	v_pk_fma_f32 v[104:105], v[104:105], v[172:173], v[132:133] op_sel_hi:[1,0,1]
	v_pk_fma_f32 v[106:107], v[106:107], v[172:173], v[134:135] op_sel_hi:[1,0,1]
	v_pk_fma_f32 v[92:93], v[92:93], v[174:175], v[128:129] op_sel_hi:[1,0,1]
	v_pk_fma_f32 v[94:95], v[94:95], v[174:175], v[130:131] op_sel_hi:[1,0,1]
	v_pk_fma_f32 v[88:89], v[88:89], v[174:175], v[132:133] op_sel_hi:[1,0,1]
	v_pk_fma_f32 v[90:91], v[90:91], v[174:175], v[134:135] op_sel_hi:[1,0,1]
	v_pk_fma_f32 v[76:77], v[76:77], v[176:177], v[128:129] op_sel_hi:[1,0,1]
	v_pk_fma_f32 v[78:79], v[78:79], v[176:177], v[130:131] op_sel_hi:[1,0,1]
	v_pk_fma_f32 v[72:73], v[72:73], v[176:177], v[132:133] op_sel_hi:[1,0,1]
	v_pk_fma_f32 v[74:75], v[74:75], v[176:177], v[134:135] op_sel_hi:[1,0,1]
	v_cvt_pk_bf16_f32 v194, v124, v125
	v_cvt_pk_bf16_f32 v195, v126, v127
	v_cvt_pk_bf16_f32 v196, v120, v121
	v_cvt_pk_bf16_f32 v197, v122, v123
	v_cvt_pk_bf16_f32 v198, v108, v109
	v_cvt_pk_bf16_f32 v199, v110, v111
	v_cvt_pk_bf16_f32 v200, v104, v105
	v_cvt_pk_bf16_f32 v201, v106, v107
	v_cvt_pk_bf16_f32 v202, v92, v93
	v_cvt_pk_bf16_f32 v203, v94, v95
	v_cvt_pk_bf16_f32 v204, v88, v89
	v_cvt_pk_bf16_f32 v205, v90, v91
	v_cvt_pk_bf16_f32 v206, v76, v77
	v_cvt_pk_bf16_f32 v207, v78, v79
	v_cvt_pk_bf16_f32 v208, v72, v73
	v_cvt_pk_bf16_f32 v209, v74, v75
	global_store_dwordx4 v186, v[194:197], s[70:71]
	global_store_dwordx4 v187, v[198:201], s[70:71]
	global_store_dwordx4 v188, v[202:205], s[70:71]
	global_store_dwordx4 v189, v[206:209], s[70:71]
	s_nop 1
	v_pk_fma_f32 v[60:61], v[60:61], v[178:179], v[128:129] op_sel_hi:[1,0,1]
	v_pk_fma_f32 v[62:63], v[62:63], v[178:179], v[130:131] op_sel_hi:[1,0,1]
	v_pk_fma_f32 v[56:57], v[56:57], v[178:179], v[132:133] op_sel_hi:[1,0,1]
	v_pk_fma_f32 v[58:59], v[58:59], v[178:179], v[134:135] op_sel_hi:[1,0,1]
	v_pk_fma_f32 v[44:45], v[44:45], v[180:181], v[128:129] op_sel_hi:[1,0,1]
	v_pk_fma_f32 v[46:47], v[46:47], v[180:181], v[130:131] op_sel_hi:[1,0,1]
	v_pk_fma_f32 v[40:41], v[40:41], v[180:181], v[132:133] op_sel_hi:[1,0,1]
	v_pk_fma_f32 v[42:43], v[42:43], v[180:181], v[134:135] op_sel_hi:[1,0,1]
	v_pk_fma_f32 v[28:29], v[28:29], v[182:183], v[128:129] op_sel_hi:[1,0,1]
	v_pk_fma_f32 v[30:31], v[30:31], v[182:183], v[130:131] op_sel_hi:[1,0,1]
	v_pk_fma_f32 v[24:25], v[24:25], v[182:183], v[132:133] op_sel_hi:[1,0,1]
	v_pk_fma_f32 v[26:27], v[26:27], v[182:183], v[134:135] op_sel_hi:[1,0,1]
	v_pk_fma_f32 v[12:13], v[12:13], v[184:185], v[128:129] op_sel_hi:[1,0,1]
	v_pk_fma_f32 v[14:15], v[14:15], v[184:185], v[130:131] op_sel_hi:[1,0,1]
	v_pk_fma_f32 v[8:9], v[8:9], v[184:185], v[132:133] op_sel_hi:[1,0,1]
	v_pk_fma_f32 v[10:11], v[10:11], v[184:185], v[134:135] op_sel_hi:[1,0,1]
	v_cvt_pk_bf16_f32 v194, v60, v61
	v_cvt_pk_bf16_f32 v195, v62, v63
	v_cvt_pk_bf16_f32 v196, v56, v57
	v_cvt_pk_bf16_f32 v197, v58, v59
	v_cvt_pk_bf16_f32 v198, v44, v45
	v_cvt_pk_bf16_f32 v199, v46, v47
	v_cvt_pk_bf16_f32 v200, v40, v41
	v_cvt_pk_bf16_f32 v201, v42, v43
	v_cvt_pk_bf16_f32 v202, v28, v29
	v_cvt_pk_bf16_f32 v203, v30, v31
	v_cvt_pk_bf16_f32 v204, v24, v25
	v_cvt_pk_bf16_f32 v205, v26, v27
	v_cvt_pk_bf16_f32 v206, v12, v13
	v_cvt_pk_bf16_f32 v207, v14, v15
	v_cvt_pk_bf16_f32 v208, v8, v9
	v_cvt_pk_bf16_f32 v209, v10, v11
	global_store_dwordx4 v190, v[194:197], s[70:71]
	global_store_dwordx4 v191, v[198:201], s[70:71]
	global_store_dwordx4 v192, v[202:205], s[70:71]
	global_store_dwordx4 v193, v[206:209], s[70:71]
	s_nop 1
; __device__ __forceinline__ unsigned pk2(float lo, float hi) { unsigned r; asm("v_cvt_pk_bf16_f32 %0, %1, %2" : "=v"(r) : "v"(lo), "v"(hi)); return r; }
;     __device__ __forceinline__ void operator()(const f32x4 (&acc)[2][2][4][2], const pg8::Unit& u, int wr, int wc, int fr, int fq) const {
;     ...
;         const int row0 = u.pm * 256 + wr * 64 + fr, col0 = u.pn * 256 + wc * 32 + 8 * fq;
;         const float* bp = bias + (size_t)((u.pm * 256) >> 14) * 5632 + col0;
;         f32x4 cb[2][2];
; #pragma unroll
;         for (int bj = 0; bj < 2; ++bj) { cb[bj][0] = *(const f32x4*)(bp + bj * 128); cb[bj][1] = *(const f32x4*)(bp + bj * 128 + 4); }
; #pragma unroll
;         for (int ai = 0; ai < 2; ++ai)
; #pragma unroll
;             for (int m = 0; m < 4; ++m) {
;                 const int row = row0 + ai * 128 + m * 16; const float rs = row_rs(ss, row);
; #pragma unroll
;                 for (int bj = 0; bj < 2; ++bj) {
;                     if (u.pn * 256 + bj * 128 + wc * 32 >= 2592) continue;
;                     const f32x4 v0 = acc[ai][bj][m][0] * rs + cb[bj][0], v1 = acc[ai][bj][m][1] * rs + cb[bj][1];
;                     u32x4 w; w.x = pk2(v0[0], v0[1]); w.y = pk2(v0[2], v0[3]); w.z = pk2(v1[0], v1[1]); w.w = pk2(v1[2], v1[3]);
;                     *(u32x4*)(O + (size_t)row * ldc + col0 + bj * 128) = w;
;                 }
.Lepst_bj1:
	s_bitset1_b32 s0, 7
	s_cmpk_gt_i32 s0, 0xa1f
	s_cbranch_scc1 .Lepst_done
	v_pk_fma_f32 v[116:117], v[116:117], v[170:171], v[136:137] op_sel_hi:[1,0,1]
	v_pk_fma_f32 v[118:119], v[118:119], v[170:171], v[138:139] op_sel_hi:[1,0,1]
	v_pk_fma_f32 v[112:113], v[112:113], v[170:171], v[140:141] op_sel_hi:[1,0,1]
	v_pk_fma_f32 v[114:115], v[114:115], v[170:171], v[142:143] op_sel_hi:[1,0,1]
	v_pk_fma_f32 v[100:101], v[100:101], v[172:173], v[136:137] op_sel_hi:[1,0,1]
	v_pk_fma_f32 v[102:103], v[102:103], v[172:173], v[138:139] op_sel_hi:[1,0,1]
	v_pk_fma_f32 v[96:97], v[96:97], v[172:173], v[140:141] op_sel_hi:[1,0,1]
	v_pk_fma_f32 v[98:99], v[98:99], v[172:173], v[142:143] op_sel_hi:[1,0,1]
	v_pk_fma_f32 v[84:85], v[84:85], v[174:175], v[136:137] op_sel_hi:[1,0,1]
	v_pk_fma_f32 v[86:87], v[86:87], v[174:175], v[138:139] op_sel_hi:[1,0,1]
	v_pk_fma_f32 v[80:81], v[80:81], v[174:175], v[140:141] op_sel_hi:[1,0,1]
	v_pk_fma_f32 v[82:83], v[82:83], v[174:175], v[142:143] op_sel_hi:[1,0,1]
	v_pk_fma_f32 v[68:69], v[68:69], v[176:177], v[136:137] op_sel_hi:[1,0,1]
	v_pk_fma_f32 v[70:71], v[70:71], v[176:177], v[138:139] op_sel_hi:[1,0,1]
	v_pk_fma_f32 v[64:65], v[64:65], v[176:177], v[140:141] op_sel_hi:[1,0,1]
	v_pk_fma_f32 v[66:67], v[66:67], v[176:177], v[142:143] op_sel_hi:[1,0,1]
	v_cvt_pk_bf16_f32 v194, v116, v117
	v_cvt_pk_bf16_f32 v195, v118, v119
	v_cvt_pk_bf16_f32 v196, v112, v113
	v_cvt_pk_bf16_f32 v197, v114, v115
	v_cvt_pk_bf16_f32 v198, v100, v101
	v_cvt_pk_bf16_f32 v199, v102, v103
	v_cvt_pk_bf16_f32 v200, v96, v97
	v_cvt_pk_bf16_f32 v201, v98, v99
	v_cvt_pk_bf16_f32 v202, v84, v85
	v_cvt_pk_bf16_f32 v203, v86, v87
	v_cvt_pk_bf16_f32 v204, v80, v81
	v_cvt_pk_bf16_f32 v205, v82, v83
	v_cvt_pk_bf16_f32 v206, v68, v69
	v_cvt_pk_bf16_f32 v207, v70, v71
	v_cvt_pk_bf16_f32 v208, v64, v65
	v_cvt_pk_bf16_f32 v209, v66, v67
	global_store_dwordx4 v186, v[194:197], s[70:71] offset:256
	global_store_dwordx4 v187, v[198:201], s[70:71] offset:256
	global_store_dwordx4 v188, v[202:205], s[70:71] offset:256
	global_store_dwordx4 v189, v[206:209], s[70:71] offset:256
	s_nop 1
	v_pk_fma_f32 v[52:53], v[52:53], v[178:179], v[136:137] op_sel_hi:[1,0,1]
	v_pk_fma_f32 v[54:55], v[54:55], v[178:179], v[138:139] op_sel_hi:[1,0,1]
	v_pk_fma_f32 v[48:49], v[48:49], v[178:179], v[140:141] op_sel_hi:[1,0,1]
	v_pk_fma_f32 v[50:51], v[50:51], v[178:179], v[142:143] op_sel_hi:[1,0,1]
	v_pk_fma_f32 v[36:37], v[36:37], v[180:181], v[136:137] op_sel_hi:[1,0,1]
	v_pk_fma_f32 v[38:39], v[38:39], v[180:181], v[138:139] op_sel_hi:[1,0,1]
	v_pk_fma_f32 v[32:33], v[32:33], v[180:181], v[140:141] op_sel_hi:[1,0,1]
	v_pk_fma_f32 v[34:35], v[34:35], v[180:181], v[142:143] op_sel_hi:[1,0,1]
	v_pk_fma_f32 v[20:21], v[20:21], v[182:183], v[136:137] op_sel_hi:[1,0,1]
	v_pk_fma_f32 v[22:23], v[22:23], v[182:183], v[138:139] op_sel_hi:[1,0,1]
	v_pk_fma_f32 v[16:17], v[16:17], v[182:183], v[140:141] op_sel_hi:[1,0,1]
	v_pk_fma_f32 v[18:19], v[18:19], v[182:183], v[142:143] op_sel_hi:[1,0,1]
	v_pk_fma_f32 v[4:5], v[4:5], v[184:185], v[136:137] op_sel_hi:[1,0,1]
	v_pk_fma_f32 v[6:7], v[6:7], v[184:185], v[138:139] op_sel_hi:[1,0,1]
	v_pk_fma_f32 v[0:1], v[0:1], v[184:185], v[140:141] op_sel_hi:[1,0,1]
	v_pk_fma_f32 v[2:3], v[2:3], v[184:185], v[142:143] op_sel_hi:[1,0,1]
	v_cvt_pk_bf16_f32 v194, v52, v53
	v_cvt_pk_bf16_f32 v195, v54, v55
	v_cvt_pk_bf16_f32 v196, v48, v49
	v_cvt_pk_bf16_f32 v197, v50, v51
	v_cvt_pk_bf16_f32 v198, v36, v37
	v_cvt_pk_bf16_f32 v199, v38, v39
	v_cvt_pk_bf16_f32 v200, v32, v33
	v_cvt_pk_bf16_f32 v201, v34, v35
	v_cvt_pk_bf16_f32 v202, v20, v21
	v_cvt_pk_bf16_f32 v203, v22, v23
	v_cvt_pk_bf16_f32 v204, v16, v17
	v_cvt_pk_bf16_f32 v205, v18, v19
	v_cvt_pk_bf16_f32 v206, v4, v5
	v_cvt_pk_bf16_f32 v207, v6, v7
	v_cvt_pk_bf16_f32 v208, v0, v1
	v_cvt_pk_bf16_f32 v209, v2, v3
	global_store_dwordx4 v190, v[194:197], s[70:71] offset:256
	global_store_dwordx4 v191, v[198:201], s[70:71] offset:256
	global_store_dwordx4 v192, v[202:205], s[70:71] offset:256
	global_store_dwordx4 v193, v[206:209], s[70:71] offset:256
	s_nop 1
.Lepst_done:
	s_branch .LBB0_252
